# GEMM K-loop: redundant lgkmcnt(0) waits at the start of the four MFMA segments removed (the load segment already drains LDS before the barrier)
# speedup vs baseline: 1.0110x; 1.0110x over previous
; #define PG8_STAGE(bufoff, gbase, voff) do { _Pragma("unroll") for (int _i = 0; _i < 2; ++_i) \
;         __builtin_amdgcn_global_load_lds((const unsigned*)((const char*)(gbase) + (voff)[_i]), (PG8_LAS unsigned*)(lds + (bufoff) + ldsw + _i * 8192), 16, 0, 0); } while (0)
; #define PG8_LDA(dst, b, h) do { _Pragma("unroll") for (int m = 0; m < 4; ++m) _Pragma("unroll") for (int k = 0; k < 2; ++k) dst[m][k] = *(const PG8_LAS bf16x8*)(lds + PG8_SA(b, h) + aoff + m * 2048 + k * 1024); } while (0)
; #define PG8_LDB(dst, b, h) do { _Pragma("unroll") for (int n = 0; n < 2; ++n) _Pragma("unroll") for (int k = 0; k < 2; ++k) dst[n][k] = *(const PG8_LAS bf16x8*)(lds + PG8_SB(b, h) + boff + n * 2048 + k * 1024); } while (0)
; #define PG8_MMA(ai, bj, At, Bt) do { __builtin_amdgcn_s_setprio(1); _Pragma("unroll") for (int m = 0; m < 4; ++m) _Pragma("unroll") for (int n = 0; n < 2; ++n) _Pragma("unroll") for (int k = 0; k < 2; ++k) \
;         acc[ai][bj][m][n] = __builtin_amdgcn_mfma_f32_16x16x32_bf16(Bt[n][k], At[m][k], acc[ai][bj][m][n], 0, 0, 0); __builtin_amdgcn_s_setprio(0); } while (0)
; #define PG8_WAIT_V(n) asm volatile("s_waitcnt vmcnt(" #n ")" ::: "memory")
; #define PG8_WAIT_L(n) asm volatile("s_waitcnt lgkmcnt(" #n ")" ::: "memory")
; #define PG8_BAR __builtin_amdgcn_s_barrier()
; #define PG8_SCHED __builtin_amdgcn_sched_barrier(0)
; template <class Epi, class Sched, bool ALIGN_EPI = false, bool SP2 = false>
; __device__ __forceinline__ void gemm_phase(PG8_LAS unsigned char* lds, const Gemm g, const Sched& S, const Epi& E) {
;     ...
;             PG8_LDB(B0, 0, 0); PG8_LDB(B1, 0, 1); PG8_SCHED; PG8_LDA(At, 0, 0); PG8_STAGE(PG8_SA(1, 1), a1 + hstep, voffA);
;             PG8_WAIT_V(8); PG8_WAIT_L(0); PG8_BAR; PG8_MMA(0, 0, At, B0); PG8_MMA(0, 1, At, B1); PG8_BAR; PG8_SCHED;
;             PG8_LDA(At, 0, 1); PG8_STAGE(PG8_SB(0, 0), b2, voffB); PG8_STAGE(PG8_SB(0, 1), b2 + hstep, voffB); PG8_STAGE(PG8_SA(0, 0), a2, voffA);
;             PG8_WAIT_V(8); PG8_WAIT_L(0); PG8_BAR; PG8_MMA(1, 0, At, B0); PG8_MMA(1, 1, At, B1); PG8_BAR; PG8_SCHED;
.LBB0_162:
	s_add_u32 s94, s12, 1
	s_addc_u32 s95, s13, 0
	s_add_u32 s14, s12, 2
	s_addc_u32 s15, s13, 0
	s_lshl_b64 s[30:31], s[14:15], s60
	s_add_u32 s13, s10, s30
	s_addc_u32 s29, s11, s31
	s_add_u32 s30, s8, s30
	s_addc_u32 s31, s9, s31
	s_cmp_eq_u32 s2, s12
	s_cselect_b32 s92, s88, s13
	s_cselect_b32 s93, s89, s29
	s_cselect_b32 s30, s90, s30
	s_cselect_b32 s31, s91, s31
	s_add_u32 s12, s92, s20
	s_addc_u32 s13, s93, 0
	s_add_i32 s29, 0, 0x10000
	s_add_i32 s50, 0, 0x14000
	v_add_u32_e32 v140, s29, v231
	v_add_u32_e32 v156, s50, v231
	ds_read_b128 v[128:131], v140
	ds_read_b128 v[132:135], v140 offset:1024
	ds_read_b128 v[136:139], v140 offset:2048
	ds_read_b128 v[140:143], v140 offset:3072
	ds_read_b128 v[144:147], v156
	ds_read_b128 v[148:151], v156 offset:1024
	ds_read_b128 v[152:155], v156 offset:2048
	ds_read_b128 v[156:159], v156 offset:3072
	s_lshl_b64 s[94:95], s[94:95], s60
	s_add_u32 s94, s25, s94
	s_addc_u32 s95, s26, s95
	v_lshl_add_u64 v[214:215], s[94:95], 0, v[174:175]
	s_add_i32 m0, s18, 0xc000
	ds_read_b128 v[160:163], v233
	ds_read_b128 v[210:213], v233 offset:1024
	ds_read_b128 v[234:237], v233 offset:2048
	ds_read_b128 v[238:241], v233 offset:3072
	ds_read_b128 v[242:245], v233 offset:4096
	ds_read_b128 v[246:249], v233 offset:5120
	ds_read_b128 v[250:253], v233 offset:6144
	ds_read_b128 v[218:221], v233 offset:7168
	global_load_lds_dwordx4 v[214:215], off
	v_lshl_add_u64 v[214:215], s[94:95], 0, v[176:177]
	s_add_i32 m0, s18, 0xe000
	s_nop 0
	global_load_lds_dwordx4 v[214:215], off
	s_waitcnt vmcnt(8)
	s_waitcnt lgkmcnt(0)
	s_barrier
	s_setprio 1
	v_mfma_f32_16x16x32_bf16 v[124:127], v[128:131], v[160:163], v[124:127]
	v_mfma_f32_16x16x32_bf16 v[116:119], v[136:139], v[160:163], v[116:119]
	v_mfma_f32_16x16x32_bf16 v[108:111], v[128:131], v[234:237], v[108:111]
	v_mfma_f32_16x16x32_bf16 v[100:103], v[136:139], v[234:237], v[100:103]
	v_mfma_f32_16x16x32_bf16 v[92:95], v[128:131], v[242:245], v[92:95]
	v_mfma_f32_16x16x32_bf16 v[84:87], v[136:139], v[242:245], v[84:87]
	v_mfma_f32_16x16x32_bf16 v[76:79], v[128:131], v[250:253], v[76:79]
	v_mfma_f32_16x16x32_bf16 v[68:71], v[136:139], v[250:253], v[68:71]
	v_mfma_f32_16x16x32_bf16 v[124:127], v[132:135], v[210:213], v[124:127]
	v_mfma_f32_16x16x32_bf16 v[116:119], v[140:143], v[210:213], v[116:119]
	v_mfma_f32_16x16x32_bf16 v[108:111], v[132:135], v[238:241], v[108:111]
	v_mfma_f32_16x16x32_bf16 v[100:103], v[140:143], v[238:241], v[100:103]
	v_mfma_f32_16x16x32_bf16 v[92:95], v[132:135], v[246:249], v[92:95]
	v_mfma_f32_16x16x32_bf16 v[84:87], v[140:143], v[246:249], v[84:87]
	v_mfma_f32_16x16x32_bf16 v[76:79], v[132:135], v[218:221], v[76:79]
	v_mfma_f32_16x16x32_bf16 v[68:71], v[140:143], v[218:221], v[68:71]
	s_setprio 0
	s_setprio 1
	v_mfma_f32_16x16x32_bf16 v[120:123], v[144:147], v[160:163], v[120:123]
	v_mfma_f32_16x16x32_bf16 v[112:115], v[152:155], v[160:163], v[112:115]
	v_mfma_f32_16x16x32_bf16 v[104:107], v[144:147], v[234:237], v[104:107]
	v_mfma_f32_16x16x32_bf16 v[96:99], v[152:155], v[234:237], v[96:99]
	v_mfma_f32_16x16x32_bf16 v[88:91], v[144:147], v[242:245], v[88:91]
	v_mfma_f32_16x16x32_bf16 v[80:83], v[152:155], v[242:245], v[80:83]
	v_mfma_f32_16x16x32_bf16 v[72:75], v[144:147], v[250:253], v[72:75]
	v_mfma_f32_16x16x32_bf16 v[64:67], v[152:155], v[250:253], v[64:67]
	v_mfma_f32_16x16x32_bf16 v[120:123], v[148:151], v[210:213], v[120:123]
	v_mfma_f32_16x16x32_bf16 v[112:115], v[156:159], v[210:213], v[112:115]
	v_mfma_f32_16x16x32_bf16 v[104:107], v[148:151], v[238:241], v[104:107]
	v_mfma_f32_16x16x32_bf16 v[96:99], v[156:159], v[238:241], v[96:99]
	v_mfma_f32_16x16x32_bf16 v[88:91], v[148:151], v[246:249], v[88:91]
	v_mfma_f32_16x16x32_bf16 v[80:83], v[156:159], v[246:249], v[80:83]
	v_mfma_f32_16x16x32_bf16 v[72:75], v[148:151], v[218:221], v[72:75]
	v_mfma_f32_16x16x32_bf16 v[64:67], v[156:159], v[218:221], v[64:67]
	s_setprio 0
	s_barrier
	s_add_i32 s29, s29, s77
	v_lshl_add_u64 v[214:215], s[30:31], 0, v[174:175]
	s_mov_b32 m0, s29
	ds_read_b128 v[160:163], v233 offset:16384
	ds_read_b128 v[210:213], v233 offset:17408
	ds_read_b128 v[218:221], v233 offset:18432
	ds_read_b128 v[234:237], v233 offset:19456
	ds_read_b128 v[238:241], v233 offset:20480
	ds_read_b128 v[242:245], v233 offset:21504
	ds_read_b128 v[246:249], v233 offset:22528
	ds_read_b128 v[250:253], v233 offset:23552
	global_load_lds_dwordx4 v[214:215], off
	s_add_i32 m0, s29, 0x2000
	s_add_u32 s94, s30, s21
	v_lshl_add_u64 v[214:215], s[30:31], 0, v[176:177]
	s_addc_u32 s95, s31, 0
	s_add_i32 s29, s50, s77
	global_load_lds_dwordx4 v[214:215], off
	v_lshl_add_u64 v[214:215], s[94:95], 0, v[174:175]
	s_mov_b32 m0, s29
	s_nop 0
	global_load_lds_dwordx4 v[214:215], off
	v_lshl_add_u64 v[214:215], s[94:95], 0, v[176:177]
	s_add_i32 m0, s29, 0x2000
	s_nop 0
	global_load_lds_dwordx4 v[214:215], off
	v_lshl_add_u64 v[214:215], s[92:93], 0, v[174:175]
	s_mov_b32 m0, s18
	s_nop 0
	global_load_lds_dwordx4 v[214:215], off
	v_lshl_add_u64 v[214:215], s[92:93], 0, v[176:177]
	s_mov_b32 m0, s19
	s_nop 0
	global_load_lds_dwordx4 v[214:215], off
	s_waitcnt vmcnt(8)
	s_waitcnt lgkmcnt(0)
	s_barrier
; #define PG8_STAGE(bufoff, gbase, voff) do { _Pragma("unroll") for (int _i = 0; _i < 2; ++_i) \
;         __builtin_amdgcn_global_load_lds((const unsigned*)((const char*)(gbase) + (voff)[_i]), (PG8_LAS unsigned*)(lds + (bufoff) + ldsw + _i * 8192), 16, 0, 0); } while (0)
; #define PG8_LDA(dst, b, h) do { _Pragma("unroll") for (int m = 0; m < 4; ++m) _Pragma("unroll") for (int k = 0; k < 2; ++k) dst[m][k] = *(const PG8_LAS bf16x8*)(lds + PG8_SA(b, h) + aoff + m * 2048 + k * 1024); } while (0)
; #define PG8_LDB(dst, b, h) do { _Pragma("unroll") for (int n = 0; n < 2; ++n) _Pragma("unroll") for (int k = 0; k < 2; ++k) dst[n][k] = *(const PG8_LAS bf16x8*)(lds + PG8_SB(b, h) + boff + n * 2048 + k * 1024); } while (0)
; #define PG8_MMA(ai, bj, At, Bt) do { __builtin_amdgcn_s_setprio(1); _Pragma("unroll") for (int m = 0; m < 4; ++m) _Pragma("unroll") for (int n = 0; n < 2; ++n) _Pragma("unroll") for (int k = 0; k < 2; ++k) \
;         acc[ai][bj][m][n] = __builtin_amdgcn_mfma_f32_16x16x32_bf16(Bt[n][k], At[m][k], acc[ai][bj][m][n], 0, 0, 0); __builtin_amdgcn_s_setprio(0); } while (0)
; #define PG8_WAIT_V(n) asm volatile("s_waitcnt vmcnt(" #n ")" ::: "memory")
; #define PG8_WAIT_L(n) asm volatile("s_waitcnt lgkmcnt(" #n ")" ::: "memory")
; #define PG8_BAR __builtin_amdgcn_s_barrier()
; #define PG8_SCHED __builtin_amdgcn_sched_barrier(0)
; template <class Epi, class Sched, bool ALIGN_EPI = false, bool SP2 = false>
; __device__ __forceinline__ void gemm_phase(PG8_LAS unsigned char* lds, const Gemm g, const Sched& S, const Epi& E) {
;     ...
;             PG8_WAIT_V(8); PG8_WAIT_L(0); PG8_BAR; PG8_MMA(1, 0, At, B0); PG8_MMA(1, 1, At, B1); PG8_BAR; PG8_SCHED;
;             PG8_LDB(B0, 1, 0); PG8_LDB(B1, 1, 1); PG8_SCHED; PG8_LDA(At, 1, 0); PG8_STAGE(PG8_SA(0, 1), a2 + hstep, voffA);
;             PG8_WAIT_V(8); PG8_WAIT_L(0); PG8_BAR; PG8_MMA(0, 0, At, B0); PG8_MMA(0, 1, At, B1); PG8_BAR; PG8_SCHED;
	s_setprio 1
	v_mfma_f32_16x16x32_bf16 v[60:63], v[128:131], v[160:163], v[60:63]
	v_mfma_f32_16x16x32_bf16 v[52:55], v[136:139], v[160:163], v[52:55]
	v_mfma_f32_16x16x32_bf16 v[44:47], v[128:131], v[218:221], v[44:47]
	v_mfma_f32_16x16x32_bf16 v[36:39], v[136:139], v[218:221], v[36:39]
	v_mfma_f32_16x16x32_bf16 v[28:31], v[128:131], v[238:241], v[28:31]
	v_mfma_f32_16x16x32_bf16 v[20:23], v[136:139], v[238:241], v[20:23]
	v_mfma_f32_16x16x32_bf16 v[12:15], v[128:131], v[246:249], v[12:15]
	v_mfma_f32_16x16x32_bf16 v[4:7], v[136:139], v[246:249], v[4:7]
	v_mfma_f32_16x16x32_bf16 v[60:63], v[132:135], v[210:213], v[60:63]
	v_mfma_f32_16x16x32_bf16 v[52:55], v[140:143], v[210:213], v[52:55]
	v_mfma_f32_16x16x32_bf16 v[44:47], v[132:135], v[234:237], v[44:47]
	v_mfma_f32_16x16x32_bf16 v[36:39], v[140:143], v[234:237], v[36:39]
	v_mfma_f32_16x16x32_bf16 v[28:31], v[132:135], v[242:245], v[28:31]
	v_mfma_f32_16x16x32_bf16 v[20:23], v[140:143], v[242:245], v[20:23]
	v_mfma_f32_16x16x32_bf16 v[12:15], v[132:135], v[250:253], v[12:15]
	v_mfma_f32_16x16x32_bf16 v[4:7], v[140:143], v[250:253], v[4:7]
	s_setprio 0
	s_setprio 1
	v_mfma_f32_16x16x32_bf16 v[56:59], v[144:147], v[160:163], v[56:59]
	v_mfma_f32_16x16x32_bf16 v[48:51], v[152:155], v[160:163], v[48:51]
	v_mfma_f32_16x16x32_bf16 v[40:43], v[144:147], v[218:221], v[40:43]
	v_mfma_f32_16x16x32_bf16 v[32:35], v[152:155], v[218:221], v[32:35]
	v_mfma_f32_16x16x32_bf16 v[24:27], v[144:147], v[238:241], v[24:27]
	v_mfma_f32_16x16x32_bf16 v[16:19], v[152:155], v[238:241], v[16:19]
	v_mfma_f32_16x16x32_bf16 v[8:11], v[144:147], v[246:249], v[8:11]
	v_mfma_f32_16x16x32_bf16 v[0:3], v[152:155], v[246:249], v[0:3]
	v_mfma_f32_16x16x32_bf16 v[56:59], v[148:151], v[210:213], v[56:59]
	v_mfma_f32_16x16x32_bf16 v[48:51], v[156:159], v[210:213], v[48:51]
	v_mfma_f32_16x16x32_bf16 v[40:43], v[148:151], v[234:237], v[40:43]
	v_mfma_f32_16x16x32_bf16 v[32:35], v[156:159], v[234:237], v[32:35]
	v_mfma_f32_16x16x32_bf16 v[24:27], v[148:151], v[242:245], v[24:27]
	v_mfma_f32_16x16x32_bf16 v[16:19], v[156:159], v[242:245], v[16:19]
	v_mfma_f32_16x16x32_bf16 v[8:11], v[148:151], v[250:253], v[8:11]
	v_mfma_f32_16x16x32_bf16 v[0:3], v[156:159], v[250:253], v[0:3]
	s_setprio 0
	s_barrier
	s_add_i32 s29, 0, 0x18000
	s_add_i32 s50, 0, 0x1c000
	v_add_u32_e32 v140, s29, v231
	v_add_u32_e32 v156, s50, v231
	ds_read_b128 v[128:131], v140
	ds_read_b128 v[132:135], v140 offset:1024
	ds_read_b128 v[136:139], v140 offset:2048
	ds_read_b128 v[140:143], v140 offset:3072
	ds_read_b128 v[144:147], v156
	ds_read_b128 v[148:151], v156 offset:1024
	ds_read_b128 v[152:155], v156 offset:2048
	ds_read_b128 v[156:159], v156 offset:3072
	s_add_u32 s92, s92, s21
	s_addc_u32 s93, s93, 0
	s_mov_b32 m0, s45
	v_lshl_add_u64 v[214:215], s[92:93], 0, v[174:175]
	ds_read_b128 v[160:163], v233 offset:32768
	ds_read_b128 v[210:213], v233 offset:33792
	ds_read_b128 v[218:221], v233 offset:34816
	ds_read_b128 v[234:237], v233 offset:35840
	ds_read_b128 v[238:241], v233 offset:36864
	ds_read_b128 v[242:245], v233 offset:37888
	ds_read_b128 v[246:249], v233 offset:38912
	ds_read_b128 v[250:253], v233 offset:39936
	global_load_lds_dwordx4 v[214:215], off
	v_lshl_add_u64 v[214:215], s[92:93], 0, v[176:177]
	s_mov_b32 m0, s57
	s_nop 0
	global_load_lds_dwordx4 v[214:215], off
	s_waitcnt vmcnt(8)
	s_waitcnt lgkmcnt(0)
	s_barrier
	s_setprio 1
	v_mfma_f32_16x16x32_bf16 v[124:127], v[128:131], v[160:163], v[124:127]
	v_mfma_f32_16x16x32_bf16 v[116:119], v[136:139], v[160:163], v[116:119]
	v_mfma_f32_16x16x32_bf16 v[108:111], v[128:131], v[218:221], v[108:111]
	v_mfma_f32_16x16x32_bf16 v[100:103], v[136:139], v[218:221], v[100:103]
	v_mfma_f32_16x16x32_bf16 v[92:95], v[128:131], v[238:241], v[92:95]
	v_mfma_f32_16x16x32_bf16 v[84:87], v[136:139], v[238:241], v[84:87]
	v_mfma_f32_16x16x32_bf16 v[76:79], v[128:131], v[246:249], v[76:79]
	v_mfma_f32_16x16x32_bf16 v[68:71], v[136:139], v[246:249], v[68:71]
	v_mfma_f32_16x16x32_bf16 v[124:127], v[132:135], v[210:213], v[124:127]
	v_mfma_f32_16x16x32_bf16 v[116:119], v[140:143], v[210:213], v[116:119]
	v_mfma_f32_16x16x32_bf16 v[108:111], v[132:135], v[234:237], v[108:111]
	v_mfma_f32_16x16x32_bf16 v[100:103], v[140:143], v[234:237], v[100:103]
	v_mfma_f32_16x16x32_bf16 v[92:95], v[132:135], v[242:245], v[92:95]
	v_mfma_f32_16x16x32_bf16 v[84:87], v[140:143], v[242:245], v[84:87]
	v_mfma_f32_16x16x32_bf16 v[76:79], v[132:135], v[250:253], v[76:79]
	v_mfma_f32_16x16x32_bf16 v[68:71], v[140:143], v[250:253], v[68:71]
	s_setprio 0
	s_setprio 1
	v_mfma_f32_16x16x32_bf16 v[120:123], v[144:147], v[160:163], v[120:123]
	v_mfma_f32_16x16x32_bf16 v[112:115], v[152:155], v[160:163], v[112:115]
	v_mfma_f32_16x16x32_bf16 v[104:107], v[144:147], v[218:221], v[104:107]
	v_mfma_f32_16x16x32_bf16 v[96:99], v[152:155], v[218:221], v[96:99]
	v_mfma_f32_16x16x32_bf16 v[88:91], v[144:147], v[238:241], v[88:91]
	v_mfma_f32_16x16x32_bf16 v[80:83], v[152:155], v[238:241], v[80:83]
	v_mfma_f32_16x16x32_bf16 v[72:75], v[144:147], v[246:249], v[72:75]
	v_mfma_f32_16x16x32_bf16 v[64:67], v[152:155], v[246:249], v[64:67]
	v_mfma_f32_16x16x32_bf16 v[120:123], v[148:151], v[210:213], v[120:123]
	v_mfma_f32_16x16x32_bf16 v[112:115], v[156:159], v[210:213], v[112:115]
	v_mfma_f32_16x16x32_bf16 v[104:107], v[148:151], v[234:237], v[104:107]
	v_mfma_f32_16x16x32_bf16 v[96:99], v[156:159], v[234:237], v[96:99]
	v_mfma_f32_16x16x32_bf16 v[88:91], v[148:151], v[242:245], v[88:91]
	v_mfma_f32_16x16x32_bf16 v[80:83], v[156:159], v[242:245], v[80:83]
	v_mfma_f32_16x16x32_bf16 v[72:75], v[148:151], v[250:253], v[72:75]
	v_mfma_f32_16x16x32_bf16 v[64:67], v[156:159], v[250:253], v[64:67]
	s_setprio 0
	s_barrier
; #define PG8_STAGE(bufoff, gbase, voff) do { _Pragma("unroll") for (int _i = 0; _i < 2; ++_i) \
;         __builtin_amdgcn_global_load_lds((const unsigned*)((const char*)(gbase) + (voff)[_i]), (PG8_LAS unsigned*)(lds + (bufoff) + ldsw + _i * 8192), 16, 0, 0); } while (0)
; #define PG8_LDA(dst, b, h) do { _Pragma("unroll") for (int m = 0; m < 4; ++m) _Pragma("unroll") for (int k = 0; k < 2; ++k) dst[m][k] = *(const PG8_LAS bf16x8*)(lds + PG8_SA(b, h) + aoff + m * 2048 + k * 1024); } while (0)
; #define PG8_MMA(ai, bj, At, Bt) do { __builtin_amdgcn_s_setprio(1); _Pragma("unroll") for (int m = 0; m < 4; ++m) _Pragma("unroll") for (int n = 0; n < 2; ++n) _Pragma("unroll") for (int k = 0; k < 2; ++k) \
;         acc[ai][bj][m][n] = __builtin_amdgcn_mfma_f32_16x16x32_bf16(Bt[n][k], At[m][k], acc[ai][bj][m][n], 0, 0, 0); __builtin_amdgcn_s_setprio(0); } while (0)
; #define PG8_WAIT_V(n) asm volatile("s_waitcnt vmcnt(" #n ")" ::: "memory")
; #define PG8_WAIT_L(n) asm volatile("s_waitcnt lgkmcnt(" #n ")" ::: "memory")
; #define PG8_BAR __builtin_amdgcn_s_barrier()
; #define PG8_SCHED __builtin_amdgcn_sched_barrier(0)
; template <class Epi, class Sched, bool ALIGN_EPI = false, bool SP2 = false>
; __device__ __forceinline__ void gemm_phase(PG8_LAS unsigned char* lds, const Gemm g, const Sched& S, const Epi& E) {
;     ...
;             PG8_LDA(At, 1, 1); PG8_STAGE(PG8_SB(1, 0), b3, voffB); PG8_STAGE(PG8_SB(1, 1), b3 + hstep, voffB); PG8_STAGE(PG8_SA(1, 0), a3, voffA);
;             PG8_WAIT_V(8); PG8_WAIT_L(0); PG8_BAR; PG8_MMA(1, 0, At, B0); PG8_MMA(1, 1, At, B1); PG8_BAR; PG8_SCHED;
	s_add_u32 s30, s30, s20
	s_addc_u32 s31, s31, 0
	s_add_i32 s29, s29, s77
	v_lshl_add_u64 v[214:215], s[30:31], 0, v[174:175]
	s_mov_b32 m0, s29
	ds_read_b128 v[160:163], v233 offset:49152
	ds_read_b128 v[210:213], v233 offset:50176
	ds_read_b128 v[218:221], v233 offset:51200
	ds_read_b128 v[234:237], v233 offset:52224
	ds_read_b128 v[238:241], v233 offset:53248
	ds_read_b128 v[242:245], v233 offset:54272
	ds_read_b128 v[246:249], v233 offset:55296
	ds_read_b128 v[250:253], v233 offset:56320
	global_load_lds_dwordx4 v[214:215], off
	s_add_i32 m0, s29, 0x2000
	v_lshl_add_u64 v[214:215], s[30:31], 0, v[176:177]
	s_add_u32 s30, s30, s21
	s_addc_u32 s31, s31, 0
	s_add_i32 s29, s50, s77
	global_load_lds_dwordx4 v[214:215], off
	v_lshl_add_u64 v[214:215], s[30:31], 0, v[174:175]
	s_mov_b32 m0, s29
	s_nop 0
	global_load_lds_dwordx4 v[214:215], off
	v_lshl_add_u64 v[214:215], s[30:31], 0, v[176:177]
	s_add_i32 m0, s29, 0x2000
	s_nop 0
	global_load_lds_dwordx4 v[214:215], off
	v_lshl_add_u64 v[214:215], s[12:13], 0, v[174:175]
	s_mov_b32 m0, s74
	s_nop 0
	global_load_lds_dwordx4 v[214:215], off
	v_lshl_add_u64 v[214:215], s[12:13], 0, v[176:177]
	s_mov_b32 m0, s75
	s_nop 0
	global_load_lds_dwordx4 v[214:215], off
	s_waitcnt vmcnt(8)
	s_waitcnt lgkmcnt(0)
	s_barrier
	s_setprio 1
	v_mfma_f32_16x16x32_bf16 v[60:63], v[128:131], v[160:163], v[60:63]
	v_mfma_f32_16x16x32_bf16 v[52:55], v[136:139], v[160:163], v[52:55]
	v_mfma_f32_16x16x32_bf16 v[44:47], v[128:131], v[218:221], v[44:47]
	v_mfma_f32_16x16x32_bf16 v[36:39], v[136:139], v[218:221], v[36:39]
	v_mfma_f32_16x16x32_bf16 v[28:31], v[128:131], v[238:241], v[28:31]
	v_mfma_f32_16x16x32_bf16 v[20:23], v[136:139], v[238:241], v[20:23]
	v_mfma_f32_16x16x32_bf16 v[12:15], v[128:131], v[246:249], v[12:15]
	v_mfma_f32_16x16x32_bf16 v[4:7], v[136:139], v[246:249], v[4:7]
	v_mfma_f32_16x16x32_bf16 v[60:63], v[132:135], v[210:213], v[60:63]
	v_mfma_f32_16x16x32_bf16 v[52:55], v[140:143], v[210:213], v[52:55]
	v_mfma_f32_16x16x32_bf16 v[44:47], v[132:135], v[234:237], v[44:47]
	v_mfma_f32_16x16x32_bf16 v[36:39], v[140:143], v[234:237], v[36:39]
	v_mfma_f32_16x16x32_bf16 v[28:31], v[132:135], v[242:245], v[28:31]
	v_mfma_f32_16x16x32_bf16 v[20:23], v[140:143], v[242:245], v[20:23]
	v_mfma_f32_16x16x32_bf16 v[12:15], v[132:135], v[250:253], v[12:15]
	v_mfma_f32_16x16x32_bf16 v[4:7], v[140:143], v[250:253], v[4:7]
	s_setprio 0
	s_setprio 1
	v_mfma_f32_16x16x32_bf16 v[56:59], v[144:147], v[160:163], v[56:59]
	v_mfma_f32_16x16x32_bf16 v[48:51], v[152:155], v[160:163], v[48:51]
	v_mfma_f32_16x16x32_bf16 v[40:43], v[144:147], v[218:221], v[40:43]
	v_mfma_f32_16x16x32_bf16 v[32:35], v[152:155], v[218:221], v[32:35]
	v_mfma_f32_16x16x32_bf16 v[24:27], v[144:147], v[238:241], v[24:27]
	v_mfma_f32_16x16x32_bf16 v[16:19], v[152:155], v[238:241], v[16:19]
	v_mfma_f32_16x16x32_bf16 v[8:11], v[144:147], v[246:249], v[8:11]
	v_mfma_f32_16x16x32_bf16 v[0:3], v[152:155], v[246:249], v[0:3]
	v_mfma_f32_16x16x32_bf16 v[56:59], v[148:151], v[210:213], v[56:59]
	v_mfma_f32_16x16x32_bf16 v[48:51], v[156:159], v[210:213], v[48:51]
	v_mfma_f32_16x16x32_bf16 v[40:43], v[148:151], v[234:237], v[40:43]
	v_mfma_f32_16x16x32_bf16 v[32:35], v[156:159], v[234:237], v[32:35]
	v_mfma_f32_16x16x32_bf16 v[24:27], v[148:151], v[242:245], v[24:27]
	v_mfma_f32_16x16x32_bf16 v[16:19], v[156:159], v[242:245], v[16:19]
	v_mfma_f32_16x16x32_bf16 v[8:11], v[148:151], v[250:253], v[8:11]
	v_mfma_f32_16x16x32_bf16 v[0:3], v[156:159], v[250:253], v[0:3]
	s_setprio 0
	s_barrier
	s_cmp_ge_u32 s14, s62
	s_mov_b64 s[12:13], s[14:15]
	s_cbranch_scc0 .LBB0_162
	s_and_b64 vcc, exec, s[86:87]
	s_cbranch_vccz .LBB0_167
	s_barrier
	s_cmp_lt_i32 s58, 1
	s_mov_b64 s[8:9], -1
	s_cbranch_scc0 .LBB0_168
